# prep S2b rewritten: gt rows via hoisted ds_read_b128, branch-free masks (on top of attention epilogue edits)
# speedup vs baseline: 1.0186x; 1.0096x over previous
.LBB0_366:
	v_and_b32_e32 v4, 31, v80
	v_readlane_b32 s2, v252, 11
	v_lshrrev_b32_e32 v52, 5, v81
	v_lshlrev_b32_e32 v5, 4, v52
	v_or_b32_e32 v0, s2, v4
	v_mul_u32_u24_e32 v0, 0x90, v0
	v_add3_u32 v61, s81, v0, v5
	ds_read_b128 v[0:3], v61
	v_readlane_b32 s3, v252, 12
	v_lshlrev_b32_e32 v52, 2, v52
	s_add_i32 s28, 0, 0x21a00
	v_or_b32_e32 v53, s3, v4
	s_movk_i32 s3, 0x90
	v_mad_u32_u24 v63, v53, s3, 0
	v_add_u32_e32 v62, v63, v5
	ds_read_b128 v[4:7], v62
	ds_read_b128 v[54:57], v61 offset:32
	ds_read_b128 v[66:69], v62 offset:32
	s_waitcnt lgkmcnt(2)
	v_mfma_f32_32x32x16_bf16 v[0:15], v[0:3], v[4:7], 0
	ds_read_b128 v[70:73], v61 offset:64
	v_or_b32_e32 v52, s2, v52
	v_lshl_add_u32 v86, v53, 2, s28
	v_lshl_add_u32 v64, v52, 2, s28
	v_readlane_b32 s2, v254, 55
	s_and_b64 vcc, exec, s[30:31]
	s_waitcnt lgkmcnt(1)
	v_mfma_f32_32x32x16_bf16 v[0:15], v[54:57], v[66:69], v[0:15]
	ds_read_b128 v[66:69], v61 offset:96
	ds_read_b128 v[74:77], v62 offset:64
	ds_read_b128 v[82:85], v62 offset:96
	s_waitcnt lgkmcnt(0)
	s_barrier
	ds_read2st64_b32 v[54:55], v86 offset0:4 offset1:5
	ds_read_b128 v[16:19], v64 offset:1024
	ds_read_b128 v[20:23], v64 offset:1056
	ds_read_b128 v[24:27], v64 offset:1088
	ds_read_b128 v[28:31], v64 offset:1120
	ds_read_b128 v[32:35], v64 offset:1280
	ds_read_b128 v[36:39], v64 offset:1312
	ds_read_b128 v[40:43], v64 offset:1344
	ds_read_b128 v[44:47], v64 offset:1376
	v_lshlrev_b32_e32 v61, 1, v53
	v_mfma_f32_32x32x16_bf16 v[0:15], v[70:73], v[74:77], v[0:15]
	v_add_u32_e32 v62, s2, v61
	v_readlane_b32 s2, v254, 56
	v_mfma_f32_32x32x16_bf16 v[0:15], v[66:69], v[82:85], v[0:15]
	v_cndmask_b32_e64 v66, 0, 1, s[30:31]
	v_cmp_ne_u32_e64 s[42:43], 1, v66
	v_add_u32_e32 v61, s2, v61
	s_movk_i32 s2, 0xff74
	v_mad_i32_i24 v63, v53, s2, v63
	s_cbranch_vccz .Lp2b_lo
	s_waitcnt lgkmcnt(0)
	v_sub_f32_e32 v16, v16, v54
	v_sub_f32_e32 v17, v17, v54
	v_sub_f32_e32 v18, v18, v54
	v_sub_f32_e32 v19, v19, v54
	v_sub_f32_e32 v20, v20, v54
	v_sub_f32_e32 v21, v21, v54
	v_sub_f32_e32 v22, v22, v54
	v_sub_f32_e32 v23, v23, v54
	v_sub_f32_e32 v24, v24, v54
	v_sub_f32_e32 v25, v25, v54
	v_sub_f32_e32 v26, v26, v54
	v_sub_f32_e32 v27, v27, v54
	v_sub_f32_e32 v28, v28, v54
	v_sub_f32_e32 v29, v29, v54
	v_sub_f32_e32 v30, v30, v54
	v_sub_f32_e32 v31, v31, v54
	v_sub_f32_e32 v32, v32, v55
	v_sub_f32_e32 v33, v33, v55
	v_sub_f32_e32 v34, v34, v55
	v_sub_f32_e32 v35, v35, v55
	v_sub_f32_e32 v36, v36, v55
	v_sub_f32_e32 v37, v37, v55
	v_sub_f32_e32 v38, v38, v55
	v_sub_f32_e32 v39, v39, v55
	v_sub_f32_e32 v40, v40, v55
	v_sub_f32_e32 v41, v41, v55
	v_sub_f32_e32 v42, v42, v55
	v_sub_f32_e32 v43, v43, v55
	v_sub_f32_e32 v44, v44, v55
	v_sub_f32_e32 v45, v45, v55
	v_sub_f32_e32 v46, v46, v55
	v_sub_f32_e32 v47, v47, v55
	v_mul_f32_e32 v16, 0x3fb8aa3b, v16
	v_mul_f32_e32 v17, 0x3fb8aa3b, v17
	v_mul_f32_e32 v18, 0x3fb8aa3b, v18
	v_mul_f32_e32 v19, 0x3fb8aa3b, v19
	v_mul_f32_e32 v20, 0x3fb8aa3b, v20
	v_mul_f32_e32 v21, 0x3fb8aa3b, v21
	v_mul_f32_e32 v22, 0x3fb8aa3b, v22
	v_mul_f32_e32 v23, 0x3fb8aa3b, v23
	v_mul_f32_e32 v24, 0x3fb8aa3b, v24
	v_mul_f32_e32 v25, 0x3fb8aa3b, v25
	v_mul_f32_e32 v26, 0x3fb8aa3b, v26
	v_mul_f32_e32 v27, 0x3fb8aa3b, v27
	v_mul_f32_e32 v28, 0x3fb8aa3b, v28
	v_mul_f32_e32 v29, 0x3fb8aa3b, v29
	v_mul_f32_e32 v30, 0x3fb8aa3b, v30
	v_mul_f32_e32 v31, 0x3fb8aa3b, v31
	v_mul_f32_e32 v32, 0x3fb8aa3b, v32
	v_mul_f32_e32 v33, 0x3fb8aa3b, v33
	v_mul_f32_e32 v34, 0x3fb8aa3b, v34
	v_mul_f32_e32 v35, 0x3fb8aa3b, v35
	v_mul_f32_e32 v36, 0x3fb8aa3b, v36
	v_mul_f32_e32 v37, 0x3fb8aa3b, v37
	v_mul_f32_e32 v38, 0x3fb8aa3b, v38
	v_mul_f32_e32 v39, 0x3fb8aa3b, v39
	v_mul_f32_e32 v40, 0x3fb8aa3b, v40
	v_mul_f32_e32 v41, 0x3fb8aa3b, v41
	v_mul_f32_e32 v42, 0x3fb8aa3b, v42
	v_mul_f32_e32 v43, 0x3fb8aa3b, v43
	v_mul_f32_e32 v44, 0x3fb8aa3b, v44
	v_mul_f32_e32 v45, 0x3fb8aa3b, v45
	v_mul_f32_e32 v46, 0x3fb8aa3b, v46
	v_mul_f32_e32 v47, 0x3fb8aa3b, v47
	v_exp_f32_e32 v16, v16
	v_exp_f32_e32 v32, v32
	v_exp_f32_e32 v17, v17
	v_exp_f32_e32 v33, v33
	v_exp_f32_e32 v18, v18
	v_exp_f32_e32 v34, v34
	v_exp_f32_e32 v19, v19
	v_exp_f32_e32 v35, v35
	v_exp_f32_e32 v20, v20
	v_exp_f32_e32 v36, v36
	v_exp_f32_e32 v21, v21
	v_exp_f32_e32 v37, v37
	v_exp_f32_e32 v22, v22
	v_exp_f32_e32 v38, v38
	v_exp_f32_e32 v23, v23
	v_exp_f32_e32 v39, v39
	v_exp_f32_e32 v24, v24
	v_exp_f32_e32 v40, v40
	v_exp_f32_e32 v25, v25
	v_exp_f32_e32 v41, v41
	v_exp_f32_e32 v26, v26
	v_exp_f32_e32 v42, v42
	v_exp_f32_e32 v27, v27
	v_exp_f32_e32 v43, v43
	v_exp_f32_e32 v28, v28
	v_exp_f32_e32 v44, v44
	v_exp_f32_e32 v29, v29
	v_exp_f32_e32 v45, v45
	v_exp_f32_e32 v30, v30
	v_exp_f32_e32 v46, v46
	v_exp_f32_e32 v31, v31
	v_exp_f32_e32 v47, v47
	s_movk_i32 s2, 0x90
	v_mul_f32_e32 v186, v0, v16
	v_mul_f32_e32 v187, v0, v32
	v_mov_b32_e32 v188, v52
	v_cmp_ge_u32_e32 vcc, v188, v53
	v_cmp_ge_u32_e64 s[4:5], v53, v188
	v_cvt_pk_bf16_f32 v186, v186, v187
	v_mad_u32_u24 v189, v188, s2, v62
	v_mad_u32_u24 v190, v188, s2, v61
	v_cndmask_b32_e32 v187, 0, v186, vcc
	v_cndmask_b32_e64 v186, 0, v186, s[4:5]
	ds_write_b16 v189, v187
	ds_write_b16_d16_hi v190, v186
	v_mul_f32_e32 v191, v1, v17
	v_mul_f32_e32 v192, v1, v33
	v_or_b32_e32 v193, 1, v52
	v_cmp_ge_u32_e32 vcc, v193, v53
	v_cmp_ge_u32_e64 s[4:5], v53, v193
	v_cvt_pk_bf16_f32 v191, v191, v192
	v_mad_u32_u24 v194, v193, s2, v62
	v_mad_u32_u24 v195, v193, s2, v61
	v_cndmask_b32_e32 v192, 0, v191, vcc
	v_cndmask_b32_e64 v191, 0, v191, s[4:5]
	ds_write_b16 v194, v192
	ds_write_b16_d16_hi v195, v191
	v_mul_f32_e32 v196, v2, v18
	v_mul_f32_e32 v197, v2, v34
	v_or_b32_e32 v198, 2, v52
	v_cmp_ge_u32_e32 vcc, v198, v53
	v_cmp_ge_u32_e64 s[4:5], v53, v198
	v_cvt_pk_bf16_f32 v196, v196, v197
	v_mad_u32_u24 v199, v198, s2, v62
	v_mad_u32_u24 v200, v198, s2, v61
	v_cndmask_b32_e32 v197, 0, v196, vcc
	v_cndmask_b32_e64 v196, 0, v196, s[4:5]
	ds_write_b16 v199, v197
	ds_write_b16_d16_hi v200, v196
	v_mul_f32_e32 v201, v3, v19
	v_mul_f32_e32 v202, v3, v35
	v_or_b32_e32 v203, 3, v52
	v_cmp_ge_u32_e32 vcc, v203, v53
	v_cmp_ge_u32_e64 s[4:5], v53, v203
	v_cvt_pk_bf16_f32 v201, v201, v202
	v_mad_u32_u24 v204, v203, s2, v62
	v_mad_u32_u24 v205, v203, s2, v61
	v_cndmask_b32_e32 v202, 0, v201, vcc
	v_cndmask_b32_e64 v201, 0, v201, s[4:5]
	s_waitcnt lgkmcnt(6)
	ds_write_b16 v204, v202
	ds_write_b16_d16_hi v205, v201
	v_mul_f32_e32 v186, v4, v20
	v_mul_f32_e32 v187, v4, v36
	v_or_b32_e32 v188, 8, v52
	v_cmp_ge_u32_e32 vcc, v188, v53
	v_cmp_ge_u32_e64 s[4:5], v53, v188
	v_cvt_pk_bf16_f32 v186, v186, v187
	v_mad_u32_u24 v189, v188, s2, v62
	v_mad_u32_u24 v190, v188, s2, v61
	v_cndmask_b32_e32 v187, 0, v186, vcc
	v_cndmask_b32_e64 v186, 0, v186, s[4:5]
	s_waitcnt lgkmcnt(6)
	ds_write_b16 v189, v187
	ds_write_b16_d16_hi v190, v186
	v_mul_f32_e32 v191, v5, v21
	v_mul_f32_e32 v192, v5, v37
	v_or_b32_e32 v193, 9, v52
	v_cmp_ge_u32_e32 vcc, v193, v53
	v_cmp_ge_u32_e64 s[4:5], v53, v193
	v_cvt_pk_bf16_f32 v191, v191, v192
	v_mad_u32_u24 v194, v193, s2, v62
	v_mad_u32_u24 v195, v193, s2, v61
	v_cndmask_b32_e32 v192, 0, v191, vcc
	v_cndmask_b32_e64 v191, 0, v191, s[4:5]
	s_waitcnt lgkmcnt(6)
	ds_write_b16 v194, v192
	ds_write_b16_d16_hi v195, v191
	v_mul_f32_e32 v196, v6, v22
	v_mul_f32_e32 v197, v6, v38
	v_or_b32_e32 v198, 10, v52
	v_cmp_ge_u32_e32 vcc, v198, v53
	v_cmp_ge_u32_e64 s[4:5], v53, v198
	v_cvt_pk_bf16_f32 v196, v196, v197
	v_mad_u32_u24 v199, v198, s2, v62
	v_mad_u32_u24 v200, v198, s2, v61
	v_cndmask_b32_e32 v197, 0, v196, vcc
	v_cndmask_b32_e64 v196, 0, v196, s[4:5]
	s_waitcnt lgkmcnt(6)
	ds_write_b16 v199, v197
	ds_write_b16_d16_hi v200, v196
	v_mul_f32_e32 v201, v7, v23
	v_mul_f32_e32 v202, v7, v39
	v_or_b32_e32 v203, 11, v52
	v_cmp_ge_u32_e32 vcc, v203, v53
	v_cmp_ge_u32_e64 s[4:5], v53, v203
	v_cvt_pk_bf16_f32 v201, v201, v202
	v_mad_u32_u24 v204, v203, s2, v62
	v_mad_u32_u24 v205, v203, s2, v61
	v_cndmask_b32_e32 v202, 0, v201, vcc
	v_cndmask_b32_e64 v201, 0, v201, s[4:5]
	s_waitcnt lgkmcnt(6)
	ds_write_b16 v204, v202
	ds_write_b16_d16_hi v205, v201
	v_mul_f32_e32 v186, v8, v24
	v_mul_f32_e32 v187, v8, v40
	v_or_b32_e32 v188, 16, v52
	v_cmp_ge_u32_e32 vcc, v188, v53
	v_cmp_ge_u32_e64 s[4:5], v53, v188
	v_cvt_pk_bf16_f32 v186, v186, v187
	v_mad_u32_u24 v189, v188, s2, v62
	v_mad_u32_u24 v190, v188, s2, v61
	v_cndmask_b32_e32 v187, 0, v186, vcc
	v_cndmask_b32_e64 v186, 0, v186, s[4:5]
	s_waitcnt lgkmcnt(6)
	ds_write_b16 v189, v187
	ds_write_b16_d16_hi v190, v186
	v_mul_f32_e32 v191, v9, v25
	v_mul_f32_e32 v192, v9, v41
	v_or_b32_e32 v193, 17, v52
	v_cmp_ge_u32_e32 vcc, v193, v53
	v_cmp_ge_u32_e64 s[4:5], v53, v193
	v_cvt_pk_bf16_f32 v191, v191, v192
	v_mad_u32_u24 v194, v193, s2, v62
	v_mad_u32_u24 v195, v193, s2, v61
	v_cndmask_b32_e32 v192, 0, v191, vcc
	v_cndmask_b32_e64 v191, 0, v191, s[4:5]
	s_waitcnt lgkmcnt(6)
	ds_write_b16 v194, v192
	ds_write_b16_d16_hi v195, v191
	v_mul_f32_e32 v196, v10, v26
	v_mul_f32_e32 v197, v10, v42
	v_or_b32_e32 v198, 18, v52
	v_cmp_ge_u32_e32 vcc, v198, v53
	v_cmp_ge_u32_e64 s[4:5], v53, v198
	v_cvt_pk_bf16_f32 v196, v196, v197
	v_mad_u32_u24 v199, v198, s2, v62
	v_mad_u32_u24 v200, v198, s2, v61
	v_cndmask_b32_e32 v197, 0, v196, vcc
	v_cndmask_b32_e64 v196, 0, v196, s[4:5]
	s_waitcnt lgkmcnt(6)
	ds_write_b16 v199, v197
	ds_write_b16_d16_hi v200, v196
	v_mul_f32_e32 v201, v11, v27
	v_mul_f32_e32 v202, v11, v43
	v_or_b32_e32 v203, 19, v52
	v_cmp_ge_u32_e32 vcc, v203, v53
	v_cmp_ge_u32_e64 s[4:5], v53, v203
	v_cvt_pk_bf16_f32 v201, v201, v202
	v_mad_u32_u24 v204, v203, s2, v62
	v_mad_u32_u24 v205, v203, s2, v61
	v_cndmask_b32_e32 v202, 0, v201, vcc
	v_cndmask_b32_e64 v201, 0, v201, s[4:5]
	s_waitcnt lgkmcnt(6)
	ds_write_b16 v204, v202
	ds_write_b16_d16_hi v205, v201
	v_mul_f32_e32 v186, v12, v28
	v_mul_f32_e32 v187, v12, v44
	v_or_b32_e32 v188, 24, v52
	v_cmp_ge_u32_e32 vcc, v188, v53
	v_cmp_ge_u32_e64 s[4:5], v53, v188
	v_cvt_pk_bf16_f32 v186, v186, v187
	v_mad_u32_u24 v189, v188, s2, v62
	v_mad_u32_u24 v190, v188, s2, v61
	v_cndmask_b32_e32 v187, 0, v186, vcc
	v_cndmask_b32_e64 v186, 0, v186, s[4:5]
	s_waitcnt lgkmcnt(6)
	ds_write_b16 v189, v187
	ds_write_b16_d16_hi v190, v186
	v_mul_f32_e32 v191, v13, v29
	v_mul_f32_e32 v192, v13, v45
	v_or_b32_e32 v193, 25, v52
	v_cmp_ge_u32_e32 vcc, v193, v53
	v_cmp_ge_u32_e64 s[4:5], v53, v193
	v_cvt_pk_bf16_f32 v191, v191, v192
	v_mad_u32_u24 v194, v193, s2, v62
	v_mad_u32_u24 v195, v193, s2, v61
	v_cndmask_b32_e32 v192, 0, v191, vcc
	v_cndmask_b32_e64 v191, 0, v191, s[4:5]
	s_waitcnt lgkmcnt(6)
	ds_write_b16 v194, v192
	ds_write_b16_d16_hi v195, v191
	v_mul_f32_e32 v196, v14, v30
	v_mul_f32_e32 v197, v14, v46
	v_or_b32_e32 v198, 26, v52
	v_cmp_ge_u32_e32 vcc, v198, v53
	v_cmp_ge_u32_e64 s[4:5], v53, v198
	v_cvt_pk_bf16_f32 v196, v196, v197
	v_mad_u32_u24 v199, v198, s2, v62
	v_mad_u32_u24 v200, v198, s2, v61
	v_cndmask_b32_e32 v197, 0, v196, vcc
	v_cndmask_b32_e64 v196, 0, v196, s[4:5]
	s_waitcnt lgkmcnt(6)
	ds_write_b16 v199, v197
	ds_write_b16_d16_hi v200, v196
	v_mul_f32_e32 v201, v15, v31
	v_mul_f32_e32 v202, v15, v47
	v_or_b32_e32 v203, 27, v52
	v_cmp_ge_u32_e32 vcc, v203, v53
	v_cmp_ge_u32_e64 s[4:5], v53, v203
	v_cvt_pk_bf16_f32 v201, v201, v202
	v_mad_u32_u24 v204, v203, s2, v62
	v_mad_u32_u24 v205, v203, s2, v61
	v_cndmask_b32_e32 v202, 0, v201, vcc
	v_cndmask_b32_e64 v201, 0, v201, s[4:5]
	s_waitcnt lgkmcnt(6)
	ds_write_b16 v204, v202
	ds_write_b16_d16_hi v205, v201
	s_branch .LBB0_494
.Lp2b_lo:
	ds_read_b128 v[154:157], v64 offset:512
	ds_read_b128 v[158:161], v64 offset:544
	ds_read_b128 v[162:165], v64 offset:576
	ds_read_b128 v[166:169], v64 offset:608
	s_waitcnt lgkmcnt(4)
	ds_read_b128 v[170:173], v64 offset:768
	ds_read_b128 v[174:177], v64 offset:800
	ds_read_b128 v[178:181], v64 offset:832
	ds_read_b128 v[182:185], v64 offset:864
	v_sub_f32_e32 v16, v16, v54
	v_sub_f32_e32 v17, v17, v54
	v_sub_f32_e32 v18, v18, v54
	v_sub_f32_e32 v19, v19, v54
	v_sub_f32_e32 v20, v20, v54
	v_sub_f32_e32 v21, v21, v54
	v_sub_f32_e32 v22, v22, v54
	v_sub_f32_e32 v23, v23, v54
	v_sub_f32_e32 v24, v24, v54
	v_sub_f32_e32 v25, v25, v54
	v_sub_f32_e32 v26, v26, v54
	v_sub_f32_e32 v27, v27, v54
	v_sub_f32_e32 v28, v28, v54
	v_sub_f32_e32 v29, v29, v54
	v_sub_f32_e32 v30, v30, v54
	v_sub_f32_e32 v31, v31, v54
	v_sub_f32_e32 v32, v32, v55
	v_sub_f32_e32 v33, v33, v55
	v_sub_f32_e32 v34, v34, v55
	v_sub_f32_e32 v35, v35, v55
	v_sub_f32_e32 v36, v36, v55
	v_sub_f32_e32 v37, v37, v55
	v_sub_f32_e32 v38, v38, v55
	v_sub_f32_e32 v39, v39, v55
	v_sub_f32_e32 v40, v40, v55
	v_sub_f32_e32 v41, v41, v55
	v_sub_f32_e32 v42, v42, v55
	v_sub_f32_e32 v43, v43, v55
	v_sub_f32_e32 v44, v44, v55
	v_sub_f32_e32 v45, v45, v55
	v_sub_f32_e32 v46, v46, v55
	v_sub_f32_e32 v47, v47, v55
	v_mul_f32_e32 v16, 0x3fb8aa3b, v16
	v_mul_f32_e32 v17, 0x3fb8aa3b, v17
	v_mul_f32_e32 v18, 0x3fb8aa3b, v18
	v_mul_f32_e32 v19, 0x3fb8aa3b, v19
	v_mul_f32_e32 v20, 0x3fb8aa3b, v20
	v_mul_f32_e32 v21, 0x3fb8aa3b, v21
	v_mul_f32_e32 v22, 0x3fb8aa3b, v22
	v_mul_f32_e32 v23, 0x3fb8aa3b, v23
	v_mul_f32_e32 v24, 0x3fb8aa3b, v24
	v_mul_f32_e32 v25, 0x3fb8aa3b, v25
	v_mul_f32_e32 v26, 0x3fb8aa3b, v26
	v_mul_f32_e32 v27, 0x3fb8aa3b, v27
	v_mul_f32_e32 v28, 0x3fb8aa3b, v28
	v_mul_f32_e32 v29, 0x3fb8aa3b, v29
	v_mul_f32_e32 v30, 0x3fb8aa3b, v30
	v_mul_f32_e32 v31, 0x3fb8aa3b, v31
	v_mul_f32_e32 v32, 0x3fb8aa3b, v32
	v_mul_f32_e32 v33, 0x3fb8aa3b, v33
	v_mul_f32_e32 v34, 0x3fb8aa3b, v34
	v_mul_f32_e32 v35, 0x3fb8aa3b, v35
	v_mul_f32_e32 v36, 0x3fb8aa3b, v36
	v_mul_f32_e32 v37, 0x3fb8aa3b, v37
	v_mul_f32_e32 v38, 0x3fb8aa3b, v38
	v_mul_f32_e32 v39, 0x3fb8aa3b, v39
	v_mul_f32_e32 v40, 0x3fb8aa3b, v40
	v_mul_f32_e32 v41, 0x3fb8aa3b, v41
	v_mul_f32_e32 v42, 0x3fb8aa3b, v42
	v_mul_f32_e32 v43, 0x3fb8aa3b, v43
	v_mul_f32_e32 v44, 0x3fb8aa3b, v44
	v_mul_f32_e32 v45, 0x3fb8aa3b, v45
	v_mul_f32_e32 v46, 0x3fb8aa3b, v46
	v_mul_f32_e32 v47, 0x3fb8aa3b, v47
	v_exp_f32_e32 v16, v16
	v_exp_f32_e32 v32, v32
	v_exp_f32_e32 v17, v17
	v_exp_f32_e32 v33, v33
	v_exp_f32_e32 v18, v18
	v_exp_f32_e32 v34, v34
	v_exp_f32_e32 v19, v19
	v_exp_f32_e32 v35, v35
	v_exp_f32_e32 v20, v20
	v_exp_f32_e32 v36, v36
	v_exp_f32_e32 v21, v21
	v_exp_f32_e32 v37, v37
	v_exp_f32_e32 v22, v22
	v_exp_f32_e32 v38, v38
	v_exp_f32_e32 v23, v23
	v_exp_f32_e32 v39, v39
	v_exp_f32_e32 v24, v24
	v_exp_f32_e32 v40, v40
	v_exp_f32_e32 v25, v25
	v_exp_f32_e32 v41, v41
	v_exp_f32_e32 v26, v26
	v_exp_f32_e32 v42, v42
	v_exp_f32_e32 v27, v27
	v_exp_f32_e32 v43, v43
	v_exp_f32_e32 v28, v28
	v_exp_f32_e32 v44, v44
	v_exp_f32_e32 v29, v29
	v_exp_f32_e32 v45, v45
	v_exp_f32_e32 v30, v30
	v_exp_f32_e32 v46, v46
	v_exp_f32_e32 v31, v31
	v_exp_f32_e32 v47, v47
	s_movk_i32 s2, 0xfff
	s_waitcnt lgkmcnt(0)
	v_mov_b32_e32 v188, v52
	v_mul_f32_e64 v186, v0, -v154
	v_mul_f32_e64 v187, v0, -v170
	v_cmp_gt_u32_e32 vcc, v188, v53
	v_cmp_lt_u32_e64 s[4:5], v188, v53
	v_mul_f32_e32 v186, v16, v186
	v_mul_f32_e32 v187, v32, v187
	v_lshl_add_u32 v189, v188, 8, v63
	v_lshlrev_b32_e32 v190, 6, v188
	v_bitop3_b32 v190, v190, s2, v53 bitop3:0x36
	v_cndmask_b32_e32 v186, 0, v186, vcc
	v_cndmask_b32_e64 v187, 0, v187, s[4:5]
	v_lshl_add_u32 v190, v190, 2, 0
	v_add_u32_e32 v190, 0x10a00, v190
	ds_write_b32 v189, v186 offset:51712
	ds_write_b32 v190, v187
	v_or_b32_e32 v193, 1, v52
	v_mul_f32_e64 v191, v1, -v155
	v_mul_f32_e64 v192, v1, -v171
	v_cmp_gt_u32_e32 vcc, v193, v53
	v_cmp_lt_u32_e64 s[4:5], v193, v53
	v_mul_f32_e32 v191, v17, v191
	v_mul_f32_e32 v192, v33, v192
	v_lshl_add_u32 v194, v193, 8, v63
	v_lshlrev_b32_e32 v195, 6, v193
	v_bitop3_b32 v195, v195, s2, v53 bitop3:0x36
	v_cndmask_b32_e32 v191, 0, v191, vcc
	v_cndmask_b32_e64 v192, 0, v192, s[4:5]
	v_lshl_add_u32 v195, v195, 2, 0
	v_add_u32_e32 v195, 0x10a00, v195
	ds_write_b32 v194, v191 offset:51712
	ds_write_b32 v195, v192
	v_or_b32_e32 v198, 2, v52
	v_mul_f32_e64 v196, v2, -v156
	v_mul_f32_e64 v197, v2, -v172
	v_cmp_gt_u32_e32 vcc, v198, v53
	v_cmp_lt_u32_e64 s[4:5], v198, v53
	v_mul_f32_e32 v196, v18, v196
	v_mul_f32_e32 v197, v34, v197
	v_lshl_add_u32 v199, v198, 8, v63
	v_lshlrev_b32_e32 v200, 6, v198
	v_bitop3_b32 v200, v200, s2, v53 bitop3:0x36
	v_cndmask_b32_e32 v196, 0, v196, vcc
	v_cndmask_b32_e64 v197, 0, v197, s[4:5]
	v_lshl_add_u32 v200, v200, 2, 0
	v_add_u32_e32 v200, 0x10a00, v200
	ds_write_b32 v199, v196 offset:51712
	ds_write_b32 v200, v197
	v_or_b32_e32 v203, 3, v52
	v_mul_f32_e64 v201, v3, -v157
	v_mul_f32_e64 v202, v3, -v173
	v_cmp_gt_u32_e32 vcc, v203, v53
	v_cmp_lt_u32_e64 s[4:5], v203, v53
	v_mul_f32_e32 v201, v19, v201
	v_mul_f32_e32 v202, v35, v202
	v_lshl_add_u32 v204, v203, 8, v63
	v_lshlrev_b32_e32 v205, 6, v203
	v_bitop3_b32 v205, v205, s2, v53 bitop3:0x36
	v_cndmask_b32_e32 v201, 0, v201, vcc
	v_cndmask_b32_e64 v202, 0, v202, s[4:5]
	v_lshl_add_u32 v205, v205, 2, 0
	v_add_u32_e32 v205, 0x10a00, v205
	s_waitcnt lgkmcnt(6)
	ds_write_b32 v204, v201 offset:51712
	ds_write_b32 v205, v202
	v_or_b32_e32 v188, 8, v52
	v_mul_f32_e64 v186, v4, -v158
	v_mul_f32_e64 v187, v4, -v174
	v_cmp_gt_u32_e32 vcc, v188, v53
	v_cmp_lt_u32_e64 s[4:5], v188, v53
	v_mul_f32_e32 v186, v20, v186
	v_mul_f32_e32 v187, v36, v187
	v_lshl_add_u32 v189, v188, 8, v63
	v_lshlrev_b32_e32 v190, 6, v188
	v_bitop3_b32 v190, v190, s2, v53 bitop3:0x36
	v_cndmask_b32_e32 v186, 0, v186, vcc
	v_cndmask_b32_e64 v187, 0, v187, s[4:5]
	v_lshl_add_u32 v190, v190, 2, 0
	v_add_u32_e32 v190, 0x10a00, v190
	s_waitcnt lgkmcnt(6)
	ds_write_b32 v189, v186 offset:51712
	ds_write_b32 v190, v187
	v_or_b32_e32 v193, 9, v52
	v_mul_f32_e64 v191, v5, -v159
	v_mul_f32_e64 v192, v5, -v175
	v_cmp_gt_u32_e32 vcc, v193, v53
	v_cmp_lt_u32_e64 s[4:5], v193, v53
	v_mul_f32_e32 v191, v21, v191
	v_mul_f32_e32 v192, v37, v192
	v_lshl_add_u32 v194, v193, 8, v63
	v_lshlrev_b32_e32 v195, 6, v193
	v_bitop3_b32 v195, v195, s2, v53 bitop3:0x36
	v_cndmask_b32_e32 v191, 0, v191, vcc
	v_cndmask_b32_e64 v192, 0, v192, s[4:5]
	v_lshl_add_u32 v195, v195, 2, 0
	v_add_u32_e32 v195, 0x10a00, v195
	s_waitcnt lgkmcnt(6)
	ds_write_b32 v194, v191 offset:51712
	ds_write_b32 v195, v192
	v_or_b32_e32 v198, 10, v52
	v_mul_f32_e64 v196, v6, -v160
	v_mul_f32_e64 v197, v6, -v176
	v_cmp_gt_u32_e32 vcc, v198, v53
	v_cmp_lt_u32_e64 s[4:5], v198, v53
	v_mul_f32_e32 v196, v22, v196
	v_mul_f32_e32 v197, v38, v197
	v_lshl_add_u32 v199, v198, 8, v63
	v_lshlrev_b32_e32 v200, 6, v198
	v_bitop3_b32 v200, v200, s2, v53 bitop3:0x36
	v_cndmask_b32_e32 v196, 0, v196, vcc
	v_cndmask_b32_e64 v197, 0, v197, s[4:5]
	v_lshl_add_u32 v200, v200, 2, 0
	v_add_u32_e32 v200, 0x10a00, v200
	s_waitcnt lgkmcnt(6)
	ds_write_b32 v199, v196 offset:51712
	ds_write_b32 v200, v197
	v_or_b32_e32 v203, 11, v52
	v_mul_f32_e64 v201, v7, -v161
	v_mul_f32_e64 v202, v7, -v177
	v_cmp_gt_u32_e32 vcc, v203, v53
	v_cmp_lt_u32_e64 s[4:5], v203, v53
	v_mul_f32_e32 v201, v23, v201
	v_mul_f32_e32 v202, v39, v202
	v_lshl_add_u32 v204, v203, 8, v63
	v_lshlrev_b32_e32 v205, 6, v203
	v_bitop3_b32 v205, v205, s2, v53 bitop3:0x36
	v_cndmask_b32_e32 v201, 0, v201, vcc
	v_cndmask_b32_e64 v202, 0, v202, s[4:5]
	v_lshl_add_u32 v205, v205, 2, 0
	v_add_u32_e32 v205, 0x10a00, v205
	s_waitcnt lgkmcnt(6)
	ds_write_b32 v204, v201 offset:51712
	ds_write_b32 v205, v202
	v_or_b32_e32 v188, 16, v52
	v_mul_f32_e64 v186, v8, -v162
	v_mul_f32_e64 v187, v8, -v178
	v_cmp_gt_u32_e32 vcc, v188, v53
	v_cmp_lt_u32_e64 s[4:5], v188, v53
	v_mul_f32_e32 v186, v24, v186
	v_mul_f32_e32 v187, v40, v187
	v_lshl_add_u32 v189, v188, 8, v63
	v_lshlrev_b32_e32 v190, 6, v188
	v_bitop3_b32 v190, v190, s2, v53 bitop3:0x36
	v_cndmask_b32_e32 v186, 0, v186, vcc
	v_cndmask_b32_e64 v187, 0, v187, s[4:5]
	v_lshl_add_u32 v190, v190, 2, 0
	v_add_u32_e32 v190, 0x10a00, v190
	s_waitcnt lgkmcnt(6)
	ds_write_b32 v189, v186 offset:51712
	ds_write_b32 v190, v187
	v_or_b32_e32 v193, 17, v52
	v_mul_f32_e64 v191, v9, -v163
	v_mul_f32_e64 v192, v9, -v179
	v_cmp_gt_u32_e32 vcc, v193, v53
	v_cmp_lt_u32_e64 s[4:5], v193, v53
	v_mul_f32_e32 v191, v25, v191
	v_mul_f32_e32 v192, v41, v192
	v_lshl_add_u32 v194, v193, 8, v63
	v_lshlrev_b32_e32 v195, 6, v193
	v_bitop3_b32 v195, v195, s2, v53 bitop3:0x36
	v_cndmask_b32_e32 v191, 0, v191, vcc
	v_cndmask_b32_e64 v192, 0, v192, s[4:5]
	v_lshl_add_u32 v195, v195, 2, 0
	v_add_u32_e32 v195, 0x10a00, v195
	s_waitcnt lgkmcnt(6)
	ds_write_b32 v194, v191 offset:51712
	ds_write_b32 v195, v192
	v_or_b32_e32 v198, 18, v52
	v_mul_f32_e64 v196, v10, -v164
	v_mul_f32_e64 v197, v10, -v180
	v_cmp_gt_u32_e32 vcc, v198, v53
	v_cmp_lt_u32_e64 s[4:5], v198, v53
	v_mul_f32_e32 v196, v26, v196
	v_mul_f32_e32 v197, v42, v197
	v_lshl_add_u32 v199, v198, 8, v63
	v_lshlrev_b32_e32 v200, 6, v198
	v_bitop3_b32 v200, v200, s2, v53 bitop3:0x36
	v_cndmask_b32_e32 v196, 0, v196, vcc
	v_cndmask_b32_e64 v197, 0, v197, s[4:5]
	v_lshl_add_u32 v200, v200, 2, 0
	v_add_u32_e32 v200, 0x10a00, v200
	s_waitcnt lgkmcnt(6)
	ds_write_b32 v199, v196 offset:51712
	ds_write_b32 v200, v197
	v_or_b32_e32 v203, 19, v52
	v_mul_f32_e64 v201, v11, -v165
	v_mul_f32_e64 v202, v11, -v181
	v_cmp_gt_u32_e32 vcc, v203, v53
	v_cmp_lt_u32_e64 s[4:5], v203, v53
	v_mul_f32_e32 v201, v27, v201
	v_mul_f32_e32 v202, v43, v202
	v_lshl_add_u32 v204, v203, 8, v63
	v_lshlrev_b32_e32 v205, 6, v203
	v_bitop3_b32 v205, v205, s2, v53 bitop3:0x36
	v_cndmask_b32_e32 v201, 0, v201, vcc
	v_cndmask_b32_e64 v202, 0, v202, s[4:5]
	v_lshl_add_u32 v205, v205, 2, 0
	v_add_u32_e32 v205, 0x10a00, v205
	s_waitcnt lgkmcnt(6)
	ds_write_b32 v204, v201 offset:51712
	ds_write_b32 v205, v202
	v_or_b32_e32 v188, 24, v52
	v_mul_f32_e64 v186, v12, -v166
	v_mul_f32_e64 v187, v12, -v182
	v_cmp_gt_u32_e32 vcc, v188, v53
	v_cmp_lt_u32_e64 s[4:5], v188, v53
	v_mul_f32_e32 v186, v28, v186
	v_mul_f32_e32 v187, v44, v187
	v_lshl_add_u32 v189, v188, 8, v63
	v_lshlrev_b32_e32 v190, 6, v188
	v_bitop3_b32 v190, v190, s2, v53 bitop3:0x36
	v_cndmask_b32_e32 v186, 0, v186, vcc
	v_cndmask_b32_e64 v187, 0, v187, s[4:5]
	v_lshl_add_u32 v190, v190, 2, 0
	v_add_u32_e32 v190, 0x10a00, v190
	s_waitcnt lgkmcnt(6)
	ds_write_b32 v189, v186 offset:51712
	ds_write_b32 v190, v187
	v_or_b32_e32 v193, 25, v52
	v_mul_f32_e64 v191, v13, -v167
	v_mul_f32_e64 v192, v13, -v183
	v_cmp_gt_u32_e32 vcc, v193, v53
	v_cmp_lt_u32_e64 s[4:5], v193, v53
	v_mul_f32_e32 v191, v29, v191
	v_mul_f32_e32 v192, v45, v192
	v_lshl_add_u32 v194, v193, 8, v63
	v_lshlrev_b32_e32 v195, 6, v193
	v_bitop3_b32 v195, v195, s2, v53 bitop3:0x36
	v_cndmask_b32_e32 v191, 0, v191, vcc
	v_cndmask_b32_e64 v192, 0, v192, s[4:5]
	v_lshl_add_u32 v195, v195, 2, 0
	v_add_u32_e32 v195, 0x10a00, v195
	s_waitcnt lgkmcnt(6)
	ds_write_b32 v194, v191 offset:51712
	ds_write_b32 v195, v192
	v_or_b32_e32 v198, 26, v52
	v_mul_f32_e64 v196, v14, -v168
	v_mul_f32_e64 v197, v14, -v184
	v_cmp_gt_u32_e32 vcc, v198, v53
	v_cmp_lt_u32_e64 s[4:5], v198, v53
	v_mul_f32_e32 v196, v30, v196
	v_mul_f32_e32 v197, v46, v197
	v_lshl_add_u32 v199, v198, 8, v63
	v_lshlrev_b32_e32 v200, 6, v198
	v_bitop3_b32 v200, v200, s2, v53 bitop3:0x36
	v_cndmask_b32_e32 v196, 0, v196, vcc
	v_cndmask_b32_e64 v197, 0, v197, s[4:5]
	v_lshl_add_u32 v200, v200, 2, 0
	v_add_u32_e32 v200, 0x10a00, v200
	s_waitcnt lgkmcnt(6)
	ds_write_b32 v199, v196 offset:51712
	ds_write_b32 v200, v197
	v_or_b32_e32 v203, 27, v52
	v_mul_f32_e64 v201, v15, -v169
	v_mul_f32_e64 v202, v15, -v185
	v_cmp_gt_u32_e32 vcc, v203, v53
	v_cmp_lt_u32_e64 s[4:5], v203, v53
	v_mul_f32_e32 v201, v31, v201
	v_mul_f32_e32 v202, v47, v202
	v_lshl_add_u32 v204, v203, 8, v63
	v_lshlrev_b32_e32 v205, 6, v203
	v_bitop3_b32 v205, v205, s2, v53 bitop3:0x36
	v_cndmask_b32_e32 v201, 0, v201, vcc
	v_cndmask_b32_e64 v202, 0, v202, s[4:5]
	v_lshl_add_u32 v205, v205, 2, 0
	v_add_u32_e32 v205, 0x10a00, v205
	s_waitcnt lgkmcnt(6)
	ds_write_b32 v204, v201 offset:51712
	ds_write_b32 v205, v202
